# even scans: first half-interval of both GLA and HGRN2 loops: stage2 interleaved with MFMA compute
# baseline (speedup 1.0000x reference)
; __device__ __forceinline__ float lo_bf(unsigned u) { return __uint_as_float(u << 16); }
; __device__ __forceinline__ float hi_bf(unsigned u) { return __uint_as_float(u & 0xffff0000u); }
; template <int MODE>
; __device__ void scan_unit(int swave, const Params& p, int j, int b, int h, int dir, char* shm) {
;     ...
;       if (MODE == 0) {
;         float z0 = bav0, z1 = bav1;
;         const unsigned lw[8] = {R.lr0.x, R.lr0.y, R.lr0.z, R.lr0.w, R.lr1.x, R.lr1.y, R.lr1.z, R.lr1.w};
; #pragma unroll
;         for (int e = 0; e < 8; ++e) {
;           const float a0 = lo_bf(lw[e]), a1 = hi_bf(lw[e]);
;           z0 += a0 * wa2r[4 * e] + a1 * wa2r[4 * e + 2];
;           z1 += a0 * wa2r[4 * e + 1] + a1 * wa2r[4 * e + 3];
;         }
;         g0 = (fminf(z0, 0.f) - __logf(1.f + __expf(-fabsf(z0)))) * (1.f / 16.f);
;         g1 = (fminf(z1, 0.f) - __logf(1.f + __expf(-fabsf(z1)))) * (1.f / 16.f);
;     ...
;     bf16x8 Asc = {0, 0, 0, 0, 0, 0, 0, 0};
;     if (KS == 1 || wk == 0) {
;       f32x4 sc = {0.f, 0.f, 0.f, 0.f};
; #pragma unroll
;       for (int m = 0; m < DK / 32; ++m) {
;         const bf16x8 a = *(const bf16x8*)(ktil + r * QS + m * 32 + q4 * 8);
;         const bf16x8 bb = *(const bf16x8*)(qin + r * QS + m * 32 + q4 * 8);
;         sc = __builtin_amdgcn_mfma_f32_16x16x32_bf16(a, bb, sc, 0, 0, 0);
;       }
.Llw_join_677a:
	v_and_b32_e32 v205, 0xffff0000, v8
	v_and_b32_e32 v191, 0xffff0000, v16
	v_lshlrev_b32_e32 v204, 16, v8
	v_lshlrev_b32_e32 v190, 16, v16
	v_mul_f32_e32 v206, v54, v205
	v_mul_f32_e32 v192, v54, v191
	v_mul_f32_e32 v205, v55, v205
	v_mul_f32_e32 v191, v55, v191
	v_fmac_f32_e32 v205, v53, v204
	v_fmac_f32_e32 v191, v53, v190
	v_and_b32_e32 v212, 0xffff0000, v9
	v_and_b32_e32 v198, 0xffff0000, v17
	v_fmac_f32_e32 v206, v52, v204
	v_fmac_f32_e32 v192, v52, v190
	v_add_f32_e32 v204, v81, v205
	v_add_f32_e32 v190, v81, v191
	v_lshlrev_b32_e32 v205, 16, v9
	v_lshlrev_b32_e32 v191, 16, v17
	v_mul_f32_e32 v213, v58, v212
	v_mul_f32_e32 v199, v58, v198
	v_mul_f32_e32 v212, v59, v212
	v_mul_f32_e32 v198, v59, v198
	v_fmac_f32_e32 v212, v57, v205
	v_fmac_f32_e32 v198, v57, v191
	v_add_f32_e32 v206, v80, v206
	v_add_f32_e32 v192, v80, v192
	v_fmac_f32_e32 v213, v56, v205
	v_fmac_f32_e32 v199, v56, v191
	v_add_f32_e32 v204, v212, v204
	v_add_f32_e32 v190, v198, v190
	v_and_b32_e32 v212, 0xffff0000, v10
	v_and_b32_e32 v198, 0xffff0000, v18
	v_add_f32_e32 v206, v213, v206
	v_add_f32_e32 v192, v199, v192
	v_lshlrev_b32_e32 v205, 16, v10
	v_lshlrev_b32_e32 v191, 16, v18
	v_mul_f32_e32 v213, v68, v212
	v_mul_f32_e32 v212, v69, v212
	v_mul_f32_e32 v199, v68, v198
	v_fmac_f32_e32 v212, v77, v205
	v_mul_f32_e32 v198, v69, v198
	v_fmac_f32_e32 v213, v76, v205
	v_fmac_f32_e32 v198, v77, v191
	v_add_f32_e32 v204, v212, v204
	v_fmac_f32_e32 v199, v76, v191
	v_and_b32_e32 v212, 0xffff0000, v11
	v_add_f32_e32 v190, v198, v190
	v_add_f32_e32 v206, v213, v206
	v_and_b32_e32 v198, 0xffff0000, v19
	v_lshlrev_b32_e32 v205, 16, v11
	v_add_f32_e32 v192, v199, v192
	v_mul_f32_e32 v213, v72, v212
	v_lshlrev_b32_e32 v191, 16, v19
	v_mul_f32_e32 v212, v73, v212
	v_mul_f32_e32 v199, v72, v198
	v_fmac_f32_e32 v213, v70, v205
	v_mul_f32_e32 v198, v73, v198
	v_fmac_f32_e32 v212, v71, v205
	v_fmac_f32_e32 v199, v70, v191
	v_lshlrev_b32_e32 v205, 16, v4
	v_fmac_f32_e32 v198, v71, v191
	v_and_b32_e32 v208, 0xffff0000, v4
	v_lshlrev_b32_e32 v191, 16, v12
	v_add_f32_e32 v204, v212, v204
	v_and_b32_e32 v194, 0xffff0000, v12
	v_mul_f32_e32 v212, v62, v208
	v_add_f32_e32 v190, v198, v190
	v_mul_f32_e32 v208, v63, v208
	v_mul_f32_e32 v198, v62, v194
	v_add_f32_e32 v206, v213, v206
	v_mul_f32_e32 v194, v63, v194
	v_fmac_f32_e32 v212, v60, v205
	v_fmac_f32_e32 v208, v61, v205
	v_add_f32_e32 v192, v199, v192
	v_and_b32_e32 v205, 0xffff0000, v5
	v_fmac_f32_e32 v198, v60, v191
	v_add_f32_e32 v206, v212, v206
	v_fmac_f32_e32 v194, v61, v191
	v_add_f32_e32 v212, v208, v204
	v_and_b32_e32 v191, 0xffff0000, v13
	v_lshlrev_b32_e32 v204, 16, v5
	v_add_f32_e32 v192, v198, v192
	v_mul_f32_e32 v208, v66, v205
	v_add_f32_e32 v198, v194, v190
	v_fmac_f32_e32 v208, v64, v204
	v_lshlrev_b32_e32 v190, 16, v13
	v_add_f32_e32 v206, v208, v206
	v_mul_f32_e32 v194, v66, v191
	v_mul_f32_e32 v213, v67, v205
	v_fmac_f32_e32 v194, v64, v190
	v_and_b32_e32 v209, 0xffff0000, v7
	v_add_f32_e32 v192, v194, v192
	v_and_b32_e32 v208, 0xffff0000, v6
	v_mul_f32_e32 v199, v67, v191
	v_fmac_f32_e32 v213, v65, v204
	v_and_b32_e32 v195, 0xffff0000, v15
	v_lshlrev_b32_e32 v205, 16, v7
	v_and_b32_e32 v194, 0xffff0000, v14
	v_lshlrev_b32_e32 v204, 16, v6
	ds_read_b128 v[4:7], v108 offset:2304
	ds_read_b128 v[8:11], v108
	v_fmac_f32_e32 v199, v65, v190
	v_pk_mul_f32 v[210:211], v[78:79], v[208:209]
	v_lshlrev_b32_e32 v191, 16, v15
	v_pk_mul_f32 v[208:209], v[88:89], v[208:209]
	v_lshlrev_b32_e32 v190, 16, v14
	ds_read_b128 v[12:15], v108 offset:2368
	ds_read_b128 v[218:221], v108 offset:64
	v_mov_b32_e32 v2, v3
	v_mov_b32_e32 v128, v3
	s_waitcnt lgkmcnt(2)
	v_mfma_f32_16x16x32_bf16 v[4:7], v[4:7], v[8:11], 0
	ds_read_b64 v[8:9], v109 offset:6656
	v_pk_fma_f32 v[210:211], v[74:75], v[204:205], v[210:211]
	v_pk_mul_f32 v[196:197], v[78:79], v[194:195]
	v_pk_fma_f32 v[204:205], v[86:87], v[204:205], v[208:209]
	v_pk_mul_f32 v[194:195], v[88:89], v[194:195]
	v_add_f32_e32 v206, v210, v206
	v_add_f32_e32 v206, v211, v206
	v_pk_fma_f32 v[196:197], v[74:75], v[190:191], v[196:197]
	v_mul_f32_e64 v210, |v206|, s56
	v_pk_fma_f32 v[190:191], v[86:87], v[190:191], v[194:195]
	v_exp_f32_e32 v210, v210
	v_add_f32_e32 v192, v196, v192
	v_add_f32_e32 v211, v213, v212
	v_add_f32_e32 v192, v197, v192
	v_add_f32_e32 v204, v204, v211
	v_mul_f32_e64 v196, |v192|, s56
	v_add_f32_e32 v204, v205, v204
	v_exp_f32_e32 v196, v196
	v_add_f32_e32 v208, 1.0, v210
	v_add_f32_e32 v197, v199, v198
	v_cmp_gt_f32_e64 s[36:37], s26, v208
	v_add_f32_e32 v190, v190, v197
	v_min_f32_e32 v205, 0, v206
	v_add_f32_e32 v190, v191, v190
	v_lshlrev_b32_e32 v210, 16, v116
	v_add_f32_e32 v194, 1.0, v196
	v_cndmask_b32_e64 v209, 0, 32, s[36:37]
	v_cmp_gt_f32_e32 vcc, s26, v194
	v_ldexp_f32 v208, v208, v209
	v_min_f32_e32 v191, 0, v192
	v_log_f32_e32 v208, v208
	v_lshlrev_b32_e32 v196, 16, v118
	v_mul_f32_e64 v209, |v204|, s56
	v_cndmask_b32_e64 v195, 0, 32, vcc
	v_exp_f32_e32 v209, v209
	v_ldexp_f32 v194, v194, v195
	v_min_f32_e32 v204, 0, v204
	v_log_f32_e32 v194, v194
	v_mul_f32_e32 v206, 0x3f317217, v208
	v_mul_f32_e64 v195, |v190|, s56
	v_fma_f32 v206, v208, s31, -v206
	v_fmac_f32_e32 v206, 0x3377d1cf, v208
	v_exp_f32_e32 v195, v195
	v_fmac_f32_e32 v206, 0x3f317217, v208
	v_min_f32_e32 v190, 0, v190
	v_cmp_lt_f32_e64 s[38:39], |v208|, s27
	v_mul_f32_e32 v192, 0x3f317217, v194
	v_and_b32_e32 v211, 0xffff0000, v116
	v_fma_f32 v192, v194, s31, -v192
	ds_write_b16 v104, v94 offset:30720
	v_fmac_f32_e32 v192, 0x3377d1cf, v194
	ds_write_b16_d16_hi v104, v94 offset:30760
	v_fmac_f32_e32 v192, 0x3f317217, v194
	ds_write_b16 v104, v95 offset:30800
; template <int MODE>
; __device__ void scan_unit(int swave, const Params& p, int j, int b, int h, int dir, char* shm) {
;     ...
;         g0 = (fminf(z0, 0.f) - __logf(1.f + __expf(-fabsf(z0)))) * (1.f / 16.f);
;         g1 = (fminf(z1, 0.f) - __logf(1.f + __expf(-fabsf(z1)))) * (1.f / 16.f);
;       } else {
;         const float f0 = lbv0 + (1.f - lbv0) * sigmoidf_(lo_bf(R.k)), f1 = lbv1 + (1.f - lbv1) * sigmoidf_(hi_bf(R.k));
;         g0 = __logf(fmaxf(f0, 1e-20f)); g1 = __logf(fmaxf(f1, 1e-20f));
;       }
;       float s0, s1;
;       const float cum0 = row_scan(g0, s0), cum1 = row_scan(g1, s1);
;       float q0, q1, k0, k1;
;       if (MODE == 0) { q0 = lo_bf(R.q); q1 = hi_bf(R.q); k0 = lo_bf(R.k) * 0.125f; k1 = hi_bf(R.k) * 0.125f; }
;     ...
;     bf16x8 Asc = {0, 0, 0, 0, 0, 0, 0, 0};
;     if (KS == 1 || wk == 0) {
;       f32x4 sc = {0.f, 0.f, 0.f, 0.f};
; #pragma unroll
;       for (int m = 0; m < DK / 32; ++m) {
;         const bf16x8 a = *(const bf16x8*)(ktil + r * QS + m * 32 + q4 * 8);
;         const bf16x8 bb = *(const bf16x8*)(qin + r * QS + m * 32 + q4 * 8);
;         sc = __builtin_amdgcn_mfma_f32_16x16x32_bf16(a, bb, sc, 0, 0, 0);
;       }
;       {
;         const unsigned p01 = pk2(q4 * 4 + 0 > r ? 0.f : sc[0], q4 * 4 + 1 > r ? 0.f : sc[1]);
;         const unsigned p23 = pk2(q4 * 4 + 2 > r ? 0.f : sc[2], q4 * 4 + 3 > r ? 0.f : sc[3]);
;         Asc[0] = (short)(p01 & 0xffff); Asc[1] = (short)(p01 >> 16); Asc[2] = (short)(p23 & 0xffff); Asc[3] = (short)(p23 >> 16);
;       }
;     }
;     bf16x8 Bv[NVT];
; #pragma unroll
;     for (int t = 0; t < NVT; ++t) {
;       const uint2 vv = *(const uint2*)(vT + ((vt0 + t) * 16 + r) * VS + q4 * 4);
;       Bv[t] = (bf16x8){(short)(vv.x & 0xffff), (short)(vv.x >> 16), (short)(vv.y & 0xffff), (short)(vv.y >> 16), 0, 0, 0, 0};
;     }
;     bf16x8 Aq[2];
; #pragma unroll
;     for (int m = 0; m < 2; ++m) {
;       const uint2 lo = *(const uint2*)(qin + r * QS + slab + (2 * m) * 16 + q4 * 4);
;       const uint2 hi = *(const uint2*)(qin + r * QS + slab + (2 * m + 1) * 16 + q4 * 4);
;       Aq[m] = (bf16x8){(short)(lo.x & 0xffff), (short)(lo.x >> 16), (short)(lo.y & 0xffff), (short)(lo.y >> 16),
;                        (short)(hi.x & 0xffff), (short)(hi.x >> 16), (short)(hi.y & 0xffff), (short)(hi.y >> 16)};
;     }
;     f32x4 o[NVT];
; #pragma unroll
;     for (int t = 0; t < NVT; ++t) {
	v_cmp_lt_f32_e64 s[16:17], |v194|, s27
	ds_write_b16_d16_hi v104, v95 offset:30840
	v_and_b32_e32 v197, 0xffff0000, v118
	v_cndmask_b32_e64 v206, v208, v206, s[38:39]
	v_cndmask_b32_e64 v192, v194, v192, s[16:17]
	v_cndmask_b32_e64 v208, 0, v157, s[36:37]
	v_cndmask_b32_e32 v194, 0, v157, vcc
	v_sub_f32_e32 v206, v206, v208
	v_sub_f32_e32 v192, v192, v194
	v_add_f32_e32 v208, 1.0, v209
	v_add_f32_e32 v194, 1.0, v195
	v_cmp_gt_f32_e64 s[36:37], s26, v208
	v_cmp_gt_f32_e32 vcc, s26, v194
	v_sub_f32_e32 v205, v205, v206
	v_sub_f32_e32 v191, v191, v192
	v_mul_f32_e32 v206, 0x3d800000, v205
	v_mul_f32_e32 v192, 0x3d800000, v191
	v_cndmask_b32_e64 v209, 0, 32, s[36:37]
	v_cndmask_b32_e64 v195, 0, 32, vcc
	v_ldexp_f32 v208, v208, v209
	v_ldexp_f32 v194, v194, v195
	v_log_f32_e32 v208, v208
	v_log_f32_e32 v194, v194
	v_mul_f32_e32 v209, 0x3f317217, v208
	v_fma_f32 v209, v208, s31, -v209
	v_mul_f32_e32 v195, 0x3f317217, v194
	v_fmac_f32_e32 v209, 0x3377d1cf, v208
	v_fma_f32 v195, v194, s31, -v195
	v_fmac_f32_e32 v209, 0x3f317217, v208
	v_fmac_f32_e32 v195, 0x3377d1cf, v194
	v_cmp_lt_f32_e64 s[38:39], |v208|, s27
	v_fmac_f32_e32 v195, 0x3f317217, v194
	s_nop 0
	v_cndmask_b32_e64 v208, v208, v209, s[38:39]
	v_cmp_lt_f32_e64 s[16:17], |v194|, s27
	v_cndmask_b32_e64 v209, 0, v157, s[36:37]
	s_nop 0
	v_cndmask_b32_e64 v194, v194, v195, s[16:17]
	v_sub_f32_e32 v208, v208, v209
	v_cndmask_b32_e32 v195, 0, v157, vcc
	v_sub_f32_e32 v208, v204, v208
	v_sub_f32_e32 v194, v194, v195
	v_mul_f32_e32 v209, 0x3d800000, v208
	v_sub_f32_e32 v194, v190, v194
	v_mov_b32_dpp v204, v206 row_shr:1 row_mask:0xf bank_mask:0xf bound_ctrl:1
	v_mul_f32_e32 v195, 0x3d800000, v194
	v_fmac_f32_e32 v204, 0x3d800000, v205
	v_mov_b32_dpp v190, v192 row_shr:1 row_mask:0xf bank_mask:0xf bound_ctrl:1
	v_mov_b32_dpp v205, v209 row_shr:1 row_mask:0xf bank_mask:0xf bound_ctrl:1
	v_fmac_f32_e32 v190, 0x3d800000, v191
	v_fmac_f32_e32 v205, 0x3d800000, v208
	v_mov_b32_dpp v191, v195 row_shr:1 row_mask:0xf bank_mask:0xf bound_ctrl:1
	v_add_f32_dpp v204, v204, v204 row_shr:2 row_mask:0xf bank_mask:0xf bound_ctrl:1
	v_fmac_f32_e32 v191, 0x3d800000, v194
	v_lshlrev_b32_e32 v208, 16, v117
	v_add_f32_dpp v190, v190, v190 row_shr:2 row_mask:0xf bank_mask:0xf bound_ctrl:1
	v_add_f32_dpp v205, v205, v205 row_shr:2 row_mask:0xf bank_mask:0xf bound_ctrl:1
	v_lshlrev_b32_e32 v194, 16, v119
	v_add_f32_dpp v204, v204, v204 row_shr:4 row_mask:0xf bank_mask:0xf bound_ctrl:1
	v_add_f32_dpp v191, v191, v191 row_shr:2 row_mask:0xf bank_mask:0xf bound_ctrl:1
	v_and_b32_e32 v209, 0xffff0000, v117
	v_add_f32_dpp v205, v205, v205 row_shr:4 row_mask:0xf bank_mask:0xf bound_ctrl:1
	v_add_f32_dpp v190, v190, v190 row_shr:4 row_mask:0xf bank_mask:0xf bound_ctrl:1
	v_add_f32_dpp v206, v204, v204 row_shr:8 row_mask:0xf bank_mask:0xf bound_ctrl:1
	v_and_b32_e32 v195, 0xffff0000, v119
	ds_read2_b64 v[116:119], v115 offset1:4
	ds_read2_b64 v[124:127], v115 offset0:8 offset1:12
	v_mov_b32_e32 v10, v3
	v_mov_b32_e32 v11, v3
	s_waitcnt lgkmcnt(7)
	v_mfma_f32_16x16x32_bf16 v[4:7], v[12:15], v[218:221], v[4:7]
	s_waitcnt lgkmcnt(1)
	v_bfi_b32 v118, s30, v118, v118
	s_waitcnt lgkmcnt(0)
	v_bfi_b32 v126, s30, v126, v126
	v_cvt_pk_bf16_f32 v12, v48, v49
	v_cvt_pk_bf16_f32 v13, v50, v51
	v_cvt_pk_bf16_f32 v14, v44, v45
	s_nop 0
	v_cndmask_b32_e64 v0, v4, 0, s[6:7]
	v_cndmask_b32_e64 v1, 0, v5, s[8:9]
	v_cndmask_b32_e64 v4, v6, 0, s[10:11]
	v_cndmask_b32_e64 v5, v7, 0, s[12:13]
	v_cvt_pk_bf16_f32 v0, v0, v1
	v_cvt_pk_bf16_f32 v1, v4, v5
	v_cvt_pk_bf16_f32 v15, v46, v47
	v_mov_b32_e32 v129, v3
	v_mfma_f32_16x16x32_bf16 v[4:7], v[0:3], v[8:11], 0
	v_mfma_f32_16x16x32_bf16 v[4:7], v[116:119], v[12:15], v[4:7]
	v_cvt_pk_bf16_f32 v12, v40, v41
	v_cvt_pk_bf16_f32 v13, v42, v43
	v_cvt_pk_bf16_f32 v14, v36, v37
	v_cvt_pk_bf16_f32 v15, v38, v39
	s_nop 1
	v_mfma_f32_16x16x32_bf16 v[4:7], v[124:127], v[12:15], v[4:7]
	v_add_u32_e32 v124, 0x100, v111
	s_nop 6
	v_cvt_pk_bf16_f32 v0, v4, s0
	v_cvt_pk_bf16_f32 v1, v5, s0
	ds_write_b16 v110, v0 offset:48128
	ds_write_b16 v110, v1 offset:48392
	v_cvt_pk_bf16_f32 v0, v6, s0
	ds_write_b16 v110, v0 offset:48656
	v_cvt_pk_bf16_f32 v0, v7, s0
	ds_write_b16 v110, v0 offset:48920
	ds_read2st64_b64 v[4:7], v111 offset0:9 offset1:10
	ds_read2st64_b64 v[12:15], v111 offset0:11 offset1:12
	ds_read_b128 v[218:221], v112 offset:11776
	ds_read_b128 v[116:119], v112 offset:11840
	s_waitcnt lgkmcnt(3)
	v_mov_b32_e32 v0, v4
	v_mov_b32_e32 v1, v5
	s_waitcnt lgkmcnt(1)
	v_pk_mul_f32 v[220:221], v[50:51], v[220:221]
	v_pk_mul_f32 v[218:219], v[48:49], v[218:219]
	s_waitcnt lgkmcnt(0)
	v_pk_mul_f32 v[4:5], v[44:45], v[116:117]
	ds_read_b128 v[48:51], v112 offset:11968
	v_mfma_f32_16x16x16_bf16 v[218:221], v[0:1], v[8:9], v[218:221]
	v_mov_b32_e32 v0, v6
	v_mov_b32_e32 v1, v7
	v_pk_mul_f32 v[6:7], v[46:47], v[118:119]
	ds_read_b128 v[44:47], v112 offset:11904
	s_waitcnt lgkmcnt(0)
	v_pk_mul_f32 v[42:43], v[42:43], v[46:47]
	v_mfma_f32_16x16x16_bf16 v[4:7], v[0:1], v[8:9], v[4:7]
	v_pk_mul_f32 v[40:41], v[40:41], v[44:45]
	s_nop 1
	v_mfma_f32_16x16x16_bf16 v[116:119], v[12:13], v[8:9], v[40:43]
	v_mov_b32_e32 v0, v14
	v_mov_b32_e32 v1, v15
	ds_read_b128 v[12:15], v108 offset:14336
	v_pk_mul_f32 v[38:39], v[38:39], v[50:51]
	v_pk_mul_f32 v[36:37], v[36:37], v[48:49]
	s_nop 1
	v_mfma_f32_16x16x16_bf16 v[8:11], v[0:1], v[8:9], v[36:39]
	ds_read_b128 v[36:39], v108 offset:14400
	ds_read_b128 v[40:43], v108 offset:12032
	ds_read_b128 v[44:47], v108 offset:12096
	s_waitcnt lgkmcnt(1)
	v_mfma_f32_16x16x32_bf16 v[12:15], v[12:15], v[40:43], 0
	s_waitcnt lgkmcnt(0)
; template <int MODE>
; __device__ void scan_unit(int swave, const Params& p, int j, int b, int h, int dir, char* shm) {
;     ...
;   auto row_scan = [&](float x, float& total) {
;     x += __int_as_float(__builtin_amdgcn_update_dpp(0, __float_as_int(x), 0x111, 0xf, 0xf, true));
;     x += __int_as_float(__builtin_amdgcn_update_dpp(0, __float_as_int(x), 0x112, 0xf, 0xf, true));
;     x += __int_as_float(__builtin_amdgcn_update_dpp(0, __float_as_int(x), 0x114, 0xf, 0xf, true));
;     x += __int_as_float(__builtin_amdgcn_update_dpp(0, __float_as_int(x), 0x118, 0xf, 0xf, true));
;     total = __int_as_float(__builtin_amdgcn_ds_bpermute((lane | 15) << 2, __float_as_int(x)));
;     return x;
;   };
;   auto stage2 = [&](const Raw& R, char* buf, int c) {
;     bf16_t* qin = (bf16_t*)buf; bf16_t* ktil = (bf16_t*)(buf + OFF_KT); bf16_t* koutT = (bf16_t*)(buf + OFF_KO);
;     bf16_t* vT = (bf16_t*)(buf + OFF_VT); float* dec = (float*)(buf + OFF_DEC);
;     if (MODE != 2) {
;       float g0, g1;
;       if (MODE == 0) {
;         float z0 = bav0, z1 = bav1;
;         const unsigned lw[8] = {R.lr0.x, R.lr0.y, R.lr0.z, R.lr0.w, R.lr1.x, R.lr1.y, R.lr1.z, R.lr1.w};
; #pragma unroll
;         for (int e = 0; e < 8; ++e) {
;           const float a0 = lo_bf(lw[e]), a1 = hi_bf(lw[e]);
;           z0 += a0 * wa2r[4 * e] + a1 * wa2r[4 * e + 2];
;     ...
;         const f32x4 s0 = S[2 * m][t], s1 = S[2 * m + 1][t];
;         union { unsigned u[4]; bf16x8 v; } cv;
;         cv.u[0] = pk2(s0[0], s0[1]); cv.u[1] = pk2(s0[2], s0[3]); cv.u[2] = pk2(s1[0], s1[1]); cv.u[3] = pk2(s1[2], s1[3]);
;         o[t] = __builtin_amdgcn_mfma_f32_16x16x32_bf16(Aq[m], cv.v, o[t], 0, 0, 0);
;       }
; #pragma unroll
;     for (int t = 0; t < NVT; ++t)
; #pragma unroll
;       for (int jj = 0; jj < 4; ++jj) obuf[(wk * 16 + q4 * 4 + jj) * OS + (vt0 + t) * 16 + r] = f2bf(o[t][jj]);
; #pragma unroll
;     for (int kt = 0; kt < 4; ++kt) {
;       const uint2 kk = *(const uint2*)(koutT + (slab + kt * 16 + r) * 16 + q4 * 4);
;       const bf16x8 Ak = {(short)(kk.x & 0xffff), (short)(kk.x >> 16), (short)(kk.y & 0xffff), (short)(kk.y >> 16), 0, 0, 0, 0};
;       const f32x4 dc = *(const f32x4*)(dec + slab + kt * 16 + q4 * 4);
; #pragma unroll
;       for (int t = 0; t < NVT; ++t) S[kt][t] = __builtin_amdgcn_mfma_f32_16x16x32_bf16(Ak, Bv[t], S[kt][t] * dc, 0, 0, 0);
;     }
	v_mfma_f32_16x16x32_bf16 v[12:15], v[36:39], v[44:47], v[12:15]
	v_add_u32_e32 v36, 0x2800, v115
	v_cvt_pk_bf16_f32 v44, v218, v219
	v_cvt_pk_bf16_f32 v45, v220, v221
	v_cvt_pk_bf16_f32 v46, v4, v5
	v_cvt_pk_bf16_f32 v47, v6, v7
	s_nop 2
	v_cndmask_b32_e64 v0, v12, 0, s[6:7]
	v_cndmask_b32_e64 v1, 0, v13, s[8:9]
	v_cvt_pk_bf16_f32 v0, v0, v1
	v_cndmask_b32_e64 v1, v14, 0, s[10:11]
	v_cndmask_b32_e64 v2, v15, 0, s[12:13]
	ds_read2_b64 v[12:15], v36 offset0:224 offset1:228
	ds_read2_b64 v[36:39], v36 offset0:232 offset1:236
	v_cvt_pk_bf16_f32 v1, v1, v2
	ds_read_b64 v[126:127], v109 offset:18688
	v_mov_b32_e32 v2, v3
	s_waitcnt lgkmcnt(2)
	v_bfi_b32 v14, s30, v14, v14
	s_waitcnt lgkmcnt(1)
	v_bfi_b32 v38, s30, v38, v38
	s_waitcnt lgkmcnt(0)
	v_mfma_f32_16x16x32_bf16 v[40:43], v[0:3], v[126:129], 0
	v_mfma_f32_16x16x32_bf16 v[12:15], v[12:15], v[44:47], v[40:43]
	v_mul_f32_e32 v212, 0x3fb8aa3b, v206
	v_add_f32_dpp v191, v191, v191 row_shr:4 row_mask:0xf bank_mask:0xf bound_ctrl:1
	v_add_f32_dpp v216, v205, v205 row_shr:8 row_mask:0xf bank_mask:0xf bound_ctrl:1
	s_nop 3
	v_cvt_pk_bf16_f32 v40, v116, v117
	v_add_f32_dpp v192, v190, v190 row_shr:8 row_mask:0xf bank_mask:0xf bound_ctrl:1
	v_mul_f32_e32 v213, 0x3fb8aa3b, v216
	v_cvt_pk_bf16_f32 v41, v118, v119
	v_mul_f32_e32 v198, 0x3fb8aa3b, v192
	v_exp_f32_e32 v212, v212
	v_cvt_pk_bf16_f32 v42, v8, v9
	v_add_f32_dpp v202, v191, v191 row_shr:8 row_mask:0xf bank_mask:0xf bound_ctrl:1
	v_exp_f32_e32 v213, v213
	v_mul_f32_e32 v199, 0x3fb8aa3b, v202
	v_cvt_pk_bf16_f32 v43, v10, v11
	ds_bpermute_b32 v204, v100, v206
	v_exp_f32_e32 v198, v198
	v_mfma_f32_16x16x32_bf16 v[12:15], v[36:39], v[40:43], v[12:15]
	v_mul_f32_e32 v214, 0xbfb8aa3b, v206
	v_exp_f32_e32 v199, v199
	v_mul_f32_e32 v215, 0xbfb8aa3b, v216
	s_nop 4
	v_cvt_pk_bf16_f32 v0, v12, s0
	ds_bpermute_b32 v190, v100, v192
	v_exp_f32_e32 v214, v214
	ds_write_b16 v110, v0 offset:52352
	v_mul_f32_e32 v200, 0xbfb8aa3b, v192
	v_exp_f32_e32 v215, v215
	v_mul_f32_e32 v201, 0xbfb8aa3b, v202
	v_cvt_pk_bf16_f32 v0, v13, s0
	ds_bpermute_b32 v205, v100, v216
	v_exp_f32_e32 v200, v200
	ds_write_b16 v110, v0 offset:52616
	v_pk_mul_f32 v[208:209], v[212:213], v[208:209]
	v_exp_f32_e32 v201, v201
	s_mov_b32 s38, 0x3e000000
	v_cvt_pk_bf16_f32 v0, v14, s0
	ds_bpermute_b32 v191, v100, v202
	v_cvt_pk_bf16_f32 v212, v208, v209
	ds_write_b16 v110, v0 offset:52880
	v_pk_mul_f32 v[194:195], v[198:199], v[194:195]
	v_pk_mul_f32 v[208:209], v[210:211], s[38:39] op_sel_hi:[1, 0]
	v_cvt_pk_bf16_f32 v0, v15, s0
	s_mov_b32 s16, 0x3e000000
	s_waitcnt lgkmcnt(6)
	v_sub_f32_e32 v206, v204, v206
	v_cvt_pk_bf16_f32 v198, v194, v195
	ds_write_b16 v110, v0 offset:53144
	v_pk_mul_f32 v[210:211], v[208:209], v[214:215]
	v_mul_f32_e32 v206, 0x3fb8aa3b, v206
	ds_read2st64_b64 v[12:15], v124 offset0:32 offset1:33
	v_pk_mul_f32 v[194:195], v[196:197], s[16:17] op_sel_hi:[1, 0]
	v_cvt_pk_bf16_f32 v210, v210, v211
	s_waitcnt lgkmcnt(7)
	v_sub_f32_e32 v192, v190, v192
	ds_read2st64_b64 v[36:39], v124 offset0:34 offset1:35
	ds_write2st64_b32 v101, v212, v210 offset0:141 offset1:150
	v_pk_mul_f32 v[196:197], v[194:195], v[200:201]
	ds_read_b128 v[40:43], v112 offset:23808
	v_exp_f32_e32 v206, v206
	v_mul_f32_e32 v192, 0x3fb8aa3b, v192
	s_waitcnt lgkmcnt(8)
	v_sub_f32_e32 v210, v205, v216
	ds_read_b128 v[44:47], v112 offset:23872
	v_cvt_pk_bf16_f32 v196, v196, v197
	v_mul_f32_e32 v210, 0x3fb8aa3b, v210
	s_waitcnt lgkmcnt(1)
	v_pk_mul_f32 v[220:221], v[220:221], v[42:43]
	ds_write2st64_b32 v101, v198, v196 offset0:94 offset1:103
	v_exp_f32_e32 v210, v210
	v_exp_f32_e32 v192, v192
	v_pk_mul_f32 v[218:219], v[218:219], v[40:41]
	v_mul_f32_e32 v206, v208, v206
	v_sub_f32_e32 v196, v191, v202
	s_waitcnt lgkmcnt(1)
	v_pk_mul_f32 v[6:7], v[6:7], v[46:47]
	v_cvt_pk_bf16_f32 v206, v206, s0
	v_mul_f32_e32 v196, 0x3fb8aa3b, v196
	v_pk_mul_f32 v[4:5], v[4:5], v[44:45]
	ds_write_b16 v102, v206 offset:40704
	v_exp_f32_e32 v196, v196
	v_mul_f32_e32 v206, v209, v210
	v_mfma_f32_16x16x16_bf16 v[40:43], v[12:13], v[126:127], v[218:221]
	v_mul_f32_e32 v192, v194, v192
	v_cvt_pk_bf16_f32 v206, v206, s0
	v_mov_b32_e32 v0, v14
	v_cvt_pk_bf16_f32 v192, v192, s0
	ds_write_b16 v102, v206 offset:40736
	ds_write_b16 v102, v192 offset:28672
	v_mov_b32_e32 v1, v15
	s_and_saveexec_b64 s[38:39], s[14:15]
	s_cbranch_execz .LBB0_686
	v_mul_f32_e32 v205, 0x3fb8aa3b, v205
	v_mul_f32_e32 v204, 0x3fb8aa3b, v204
	v_exp_f32_e32 v205, v205
	v_exp_f32_e32 v204, v204
	ds_write_b64 v103, v[204:205] offset:47872
; __device__ __forceinline__ unsigned pk2(float lo, float hi) { f32x2_t v = {lo, hi}; bf16x2_t b = __builtin_convertvector(v, bf16x2_t); return __builtin_bit_cast(unsigned, b); }
; __device__ __forceinline__ float lo_bf(unsigned u) { return __uint_as_float(u << 16); }
; __device__ __forceinline__ float hi_bf(unsigned u) { return __uint_as_float(u & 0xffff0000u); }
; template <int MODE>
; __device__ void scan_unit(int swave, const Params& p, int j, int b, int h, int dir, char* shm) {
;     ...
;   auto load_raw = [&](int c, Raw& R) {
;     const int tok = tokof(c, ti);
;     const bf16_t* row = P + (rowbase + tok) * LDP;
;     if (MODE == 0) {
;       R.q = *(const unsigned*)(row + E_GQ + h * 64 + dp); R.k = *(const unsigned*)(row + E_GK + h * 64 + dp);
;       const uint4* lrp = (const uint4*)(row + (dir ? E_GLB : E_GLF));
;       R.lr0 = lrp[0]; R.lr1 = lrp[1];
;       R.v = *(const uint2*)(row + E_GV + h * 128 + vg * 4);
;     ...
;     for (int kt = 0; kt < 4; ++kt) {
;       const uint2 kk = *(const uint2*)(koutT + (slab + kt * 16 + r) * 16 + q4 * 4);
;       const bf16x8 Ak = {(short)(kk.x & 0xffff), (short)(kk.x >> 16), (short)(kk.y & 0xffff), (short)(kk.y >> 16), 0, 0, 0, 0};
;       const f32x4 dc = *(const f32x4*)(dec + slab + kt * 16 + q4 * 4);
; #pragma unroll
;       for (int t = 0; t < NVT; ++t) S[kt][t] = __builtin_amdgcn_mfma_f32_16x16x32_bf16(Ak, Bv[t], S[kt][t] * dc, 0, 0, 0);
;     }
;   };
;   auto ostore = [&](int c, const bf16_t* obuf) {
;     for (int idx = tid; idx < 16 * DV / 4; idx += 512) {
;       const int i = idx / (DV / 4), cc = (idx % (DV / 4)) * 4;
;       uint2 o = *(const uint2*)(obuf + i * OS + cc);
;       if (KS == 2) {
;         const uint2 o2 = *(const uint2*)(obuf + (16 + i) * OS + cc);
;         o.x = pk2(lo_bf(o.x) + lo_bf(o2.x), hi_bf(o.x) + hi_bf(o2.x)); o.y = pk2(lo_bf(o.y) + lo_bf(o2.y), hi_bf(o.y) + hi_bf(o2.y));
;       }
;       *(uint2*)(O + (rowbase + tokof(c, i)) * OLD + cc) = o;
;     }
.LBB0_686:
	s_or_b64 exec, exec, s[38:39]
	v_mul_f32_e32 v192, v195, v196
	ds_read_b128 v[12:15], v112 offset:24000
	ds_write_b16 v104, v90 offset:42752
	v_cvt_pk_bf16_f32 v192, v192, s0
	ds_write_b16_d16_hi v104, v90 offset:42792
	v_mfma_f32_16x16x16_bf16 v[44:47], v[0:1], v[126:127], v[4:7]
	ds_write_b16 v102, v192 offset:28704
	ds_write_b16 v104, v91 offset:42832
	ds_read_b128 v[4:7], v112 offset:23936
	s_and_saveexec_b64 s[16:17], s[14:15]
	s_cbranch_execz .LBB0_684
	v_mul_f32_e32 v191, 0x3fb8aa3b, v191
	v_mul_f32_e32 v190, 0x3fb8aa3b, v190
	v_exp_f32_e32 v191, v191
	v_exp_f32_e32 v190, v190
	ds_write_b64 v103, v[190:191] offset:35840
.LBB0_684:
	s_or_b64 exec, exec, s[16:17]
	ds_write_b16_d16_hi v104, v91 offset:42872
	s_waitcnt lgkmcnt(0)
	s_barrier
	s_waitcnt lgkmcnt(0)
	v_pk_mul_f32 v[6:7], v[118:119], v[6:7]
	v_pk_mul_f32 v[4:5], v[116:117], v[4:5]
	s_nop 1
	v_mfma_f32_16x16x16_bf16 v[48:51], v[36:37], v[126:127], v[4:7]
	v_mov_b32_e32 v0, v38
	v_mov_b32_e32 v1, v39
	s_nop 0
	v_pk_mul_f32 v[6:7], v[10:11], v[14:15]
	v_pk_mul_f32 v[4:5], v[8:9], v[12:13]
	s_nop 1
	v_mfma_f32_16x16x16_bf16 v[36:39], v[0:1], v[126:127], v[4:7]
	s_add_i32 s16, s28, 0x60
	s_and_b64 s[2:3], s[2:3], exec
	s_cselect_b32 s2, s16, 0x7e0
	v_or_b32_e32 v2, s2, v99
	v_sub_u32_e32 v0, 0x7ff, v2
	v_cndmask_b32_e64 v0, v0, v2, s[0:1]
	v_ashrrev_i32_e32 v1, 31, v0
	v_lshl_add_u64 v[0:1], s[18:19], 0, v[0:1]
	v_mov_b64_e32 v[4:5], s[46:47]
	v_mad_u64_u32 v[6:7], s[2:3], v0, s53, v[4:5]
	v_mad_i32_i24 v7, v1, s53, v7
	v_lshl_add_u64 v[0:1], v[6:7], 0, s[94:95]
	v_lshl_add_u64 v[0:1], v[0:1], 0, v[82:83]
	s_mov_b32 s45, s95
	s_mov_b32 s51, s95
	v_lshl_add_u64 v[8:9], v[6:7], 0, s[44:45]
	global_load_dword v119, v[0:1], off
	global_load_dword v118, v[0:1], off offset:512
	global_load_dwordx4 v[16:19], v[8:9], off
	v_lshl_add_u64 v[0:1], v[6:7], 0, s[50:51]
	v_lshl_add_u64 v[0:1], v[0:1], 0, v[84:85]
	global_load_dwordx4 v[12:15], v[8:9], off offset:16
	global_load_dwordx2 v[94:95], v[0:1], off offset:1024
	v_or_b32_e32 v0, 16, v2
	v_sub_u32_e32 v1, 0x7ff, v0
	v_cndmask_b32_e64 v0, v1, v0, s[0:1]
	v_ashrrev_i32_e32 v1, 31, v0
	v_lshl_add_u64 v[0:1], s[18:19], 0, v[0:1]
	v_mad_u64_u32 v[4:5], s[2:3], v0, s53, v[4:5]
	v_mad_i32_i24 v5, v1, s53, v5
	v_lshl_add_u64 v[0:1], v[4:5], 0, s[94:95]
	v_lshl_add_u64 v[0:1], v[0:1], 0, v[82:83]
	v_lshl_add_u64 v[6:7], v[4:5], 0, s[44:45]
	global_load_dword v117, v[0:1], off
	global_load_dword v116, v[0:1], off offset:512
	global_load_dwordx4 v[8:11], v[6:7], off
	v_lshl_add_u64 v[0:1], v[4:5], 0, s[50:51]
	v_lshl_add_u64 v[0:1], v[0:1], 0, v[84:85]
	global_load_dwordx4 v[4:7], v[6:7], off offset:16
	s_nop 0
	global_load_dwordx2 v[90:91], v[0:1], off offset:1024
	s_and_saveexec_b64 s[2:3], s[4:5]
	s_cbranch_execz .LBB0_691
	s_sub_i32 vcc_lo, 0x7e0, s28
	s_cmp_lg_u64 s[0:1], 0
	s_cselect_b32 vcc_lo, s28, vcc_lo
	s_add_i32 vcc_lo, vcc_lo, s18
	s_lshl_b32 vcc_lo, vcc_lo, 11
	s_add_u32 s16, s48, vcc_lo
	s_addc_u32 s17, s49, 0
	v_add_u32_e32 v160, v113, v166
	v_add_u32_e32 v161, v114, v166
	ds_read_b64 v[162:163], v160
	ds_read_b64 v[164:165], v161
	s_waitcnt lgkmcnt(1)
	global_store_dwordx2 v167, v[162:163], s[16:17]
	s_waitcnt lgkmcnt(0)
	global_store_dwordx2 v168, v[164:165], s[16:17]
	s_or_b64 exec, exec, s[2:3]
	s_waitcnt vmcnt(12)
	s_branch .Llw_join_677b
